# attention loop: all 73 v_pk_add_f32 split into scalar v_add/v_sub pairs (packed f32 beside MFMAs)
# baseline (speedup 1.0000x reference)
; #define LAS __attribute__((address_space(3)))
; __device__ __forceinline__ int crow(int r, int hi) { return (r & 3) + 8 * (r >> 2) + 4 * hi; }
; __device__ __forceinline__ void attn_phase(LAS unsigned char* lds, const bf16_t* qp, const bf16_t* kvp, bf16_t* obuf, float* lse, const float* biasG, const int gi, const int rsh, const int G) {
;     ...
;         const int c0 = ((2 * j) % 3) * 4 + w;
;         int sc[5];
; #pragma unroll
;         for (int cc = 0; cc < 5; ++cc) { const int t = c0 + cc; sc[cc] = t >= 12 ? t - 12 : t; }
;         f32x16 p[5];
;         const LAS float* bt = (const LAS float*)(lds + A_BT);
;         const LAS unsigned char* kbase = lds + A_K0 + hi * KCS + r32 * 16;
; #pragma unroll
;         for (int c2 = 0; c2 < 5; c2 += 2) {
;             bf16x8 ka[4], kb[4];
; #pragma unroll
;             for (int d0 = 0; d0 < 4; ++d0) { ka[d0] = *(const LAS bf16x8*)(kbase + 2 * d0 * KCS + sc[c2] * 512); if (c2 + 1 < 5) kb[d0] = *(const LAS bf16x8*)(kbase + 2 * d0 * KCS + sc[c2 + 1 < 5 ? c2 + 1 : c2] * 512); }
; #pragma unroll
;             for (int q = 0; q < 2; ++q) { const int cc = c2 + q; if (cc < 5) { const bool dead = (np == 0) && (w + cc < 4);
;                 const LAS float* bq_ = dead ? bt + 27 - (160 + r32 - 32 * cc - 4 * hi) : bt;
; #pragma unroll
;                 for (int r = 0; r < 16; ++r) p[cc][r] = bq_[160 + r32 - 32 * cc - crow(r, hi)]; } }
;             __builtin_amdgcn_sched_barrier(0);
; #pragma unroll
;             for (int d0 = 0; d0 < 4; ++d0) {
;                 p[c2] = __builtin_amdgcn_mfma_f32_32x32x16_bf16(ka[d0], qr[d0], p[c2], 0, 0, 0);
;                 if (c2 + 1 < 5) p[c2 + 1 < 5 ? c2 + 1 : c2] = __builtin_amdgcn_mfma_f32_32x32x16_bf16(kb[d0], qr[d0], p[c2 + 1 < 5 ? c2 + 1 : c2], 0, 0, 0);
;             }
;             __builtin_amdgcn_sched_barrier(0);
;         }
.LBB0_115:
	s_lshl_b32 s2, s22, 1
	s_mulk_i32 s22, 0xac
	s_lshr_b32 s3, s22, 8
	s_mul_i32 s3, s3, 3
	s_sub_i32 s2, s2, s3
	s_lshl_b32 s2, s2, 2
	s_and_b32 s2, s2, 0xfc
	s_add_i32 s2, s10, s2
	s_add_i32 s3, s2, -12
	s_cmp_gt_i32 s2, 11
	s_cselect_b32 s27, s3, s2
	s_cmp_gt_i32 s2, 10
	s_cselect_b32 s26, -11, 1
	s_add_i32 s26, s26, s2
	s_cmp_gt_i32 s2, 9
	s_cselect_b32 s23, -10, 2
	s_add_i32 s23, s23, s2
	s_cmp_gt_i32 s2, 8
	s_cselect_b32 s22, -9, 3
	s_add_i32 s22, s22, s2
	s_cmp_gt_i32 s2, 7
	s_cselect_b32 s4, -8, 4
	s_add_i32 s4, s4, s2
	v_readlane_b32 s2, v254, 37
	v_lshl_add_u32 v0, s27, 9, v243
	s_and_b64 vcc, s[46:47], s[52:53]
	v_mov_b32_e32 v186, s2
	v_lshl_add_u32 v1, s26, 9, v243
	ds_read_b128 v[32:35], v0 offset:12320
	ds_read_b128 v[36:39], v0 offset:24640
	ds_read_b128 v[40:43], v1 offset:12320
	ds_read_b128 v[44:47], v1 offset:24640
	ds_read_b128 v[48:51], v0
	ds_read_b128 v[52:55], v0 offset:36960
	ds_read_b128 v[56:59], v1
	ds_read_b128 v[60:63], v1 offset:36960
	v_cndmask_b32_e32 v0, v186, v245, vcc
	v_lshlrev_b32_e32 v187, 2, v238
	v_add3_u32 v0, v0, v187, v250
	ds_read2_b32 v[2:3], v0 offset0:159 offset1:160
	ds_read2_b32 v[4:5], v0 offset0:157 offset1:158
	ds_read2_b32 v[6:7], v0 offset0:151 offset1:152
	ds_read2_b32 v[8:9], v0 offset0:149 offset1:150
	ds_read2_b32 v[10:11], v0 offset0:143 offset1:144
	ds_read2_b32 v[12:13], v0 offset0:141 offset1:142
	ds_read2_b32 v[14:15], v0 offset0:135 offset1:136
	ds_read2_b32 v[64:65], v0 offset0:133 offset1:134
	s_and_b64 vcc, s[46:47], s[50:51]
	s_waitcnt lgkmcnt(7)
	v_mov_b32_e32 v0, v3
	s_waitcnt lgkmcnt(6)
	v_mov_b32_e32 v3, v4
	s_waitcnt lgkmcnt(5)
	v_mov_b32_e32 v4, v7
	s_waitcnt lgkmcnt(4)
	v_mov_b32_e32 v7, v8
	s_waitcnt lgkmcnt(3)
	v_mov_b32_e32 v8, v11
	s_waitcnt lgkmcnt(2)
	v_mov_b32_e32 v11, v12
	s_waitcnt lgkmcnt(1)
	v_mov_b32_e32 v12, v15
	s_waitcnt lgkmcnt(0)
	v_mov_b32_e32 v15, v64
	v_cndmask_b32_e32 v64, v186, v246, vcc
	v_add3_u32 v78, v64, v187, v250
	v_mov_b32_e32 v1, v2
	v_mov_b32_e32 v2, v5
	v_mov_b32_e32 v5, v6
	v_mov_b32_e32 v6, v9
	v_mov_b32_e32 v9, v10
	v_mov_b32_e32 v10, v13
	v_mov_b32_e32 v13, v14
	v_mov_b32_e32 v14, v65
	ds_read2_b32 v[64:65], v78 offset0:127 offset1:128
	ds_read2_b32 v[66:67], v78 offset0:125 offset1:126
	ds_read2_b32 v[68:69], v78 offset0:119 offset1:120
	ds_read2_b32 v[70:71], v78 offset0:117 offset1:118
	ds_read2_b32 v[72:73], v78 offset0:111 offset1:112
	ds_read2_b32 v[74:75], v78 offset0:109 offset1:110
	ds_read2_b32 v[76:77], v78 offset0:103 offset1:104
	ds_read2_b32 v[78:79], v78 offset0:101 offset1:102
	s_waitcnt lgkmcnt(7)
	v_mov_b32_e32 v80, v65
	v_mov_b32_e32 v81, v64
	s_waitcnt lgkmcnt(6)
	v_mov_b32_e32 v82, v67
	v_mov_b32_e32 v83, v66
	s_waitcnt lgkmcnt(5)
	v_mov_b32_e32 v84, v69
	v_mov_b32_e32 v85, v68
	s_waitcnt lgkmcnt(4)
	v_mov_b32_e32 v86, v71
	v_mov_b32_e32 v87, v70
	s_waitcnt lgkmcnt(3)
	v_mov_b32_e32 v88, v73
	v_mov_b32_e32 v89, v72
	s_waitcnt lgkmcnt(2)
	v_mov_b32_e32 v90, v75
	v_mov_b32_e32 v91, v74
	s_waitcnt lgkmcnt(1)
	v_mov_b32_e32 v92, v77
	v_mov_b32_e32 v93, v76
	s_waitcnt lgkmcnt(0)
	v_mov_b32_e32 v94, v79
	v_mov_b32_e32 v95, v78
	v_mfma_f32_32x32x16_bf16 v[0:15], v[48:51], v[28:31], v[0:15]
	s_nop 0
	v_mfma_f32_32x32x16_bf16 v[80:95], v[56:59], v[28:31], v[80:95]
	v_mfma_f32_32x32x16_bf16 v[0:15], v[32:35], v[24:27], v[0:15]
	v_mfma_f32_32x32x16_bf16 v[80:95], v[40:43], v[24:27], v[80:95]
	v_mfma_f32_32x32x16_bf16 v[0:15], v[36:39], v[20:23], v[0:15]
	v_mfma_f32_32x32x16_bf16 v[80:95], v[44:47], v[20:23], v[80:95]
	v_mfma_f32_32x32x16_bf16 v[0:15], v[52:55], v[16:19], v[0:15]
	v_mfma_f32_32x32x16_bf16 v[80:95], v[60:63], v[16:19], v[80:95]
	v_lshl_add_u32 v48, s23, 9, v243
	s_and_b64 vcc, s[46:47], s[0:1]
	v_lshl_add_u32 v49, s22, 9, v243
	ds_read_b128 v[32:35], v48 offset:12320
	ds_read_b128 v[36:39], v48 offset:24640
	ds_read_b128 v[40:43], v49 offset:12320
	ds_read_b128 v[44:47], v49 offset:24640
	ds_read_b128 v[182:185], v48
	ds_read_b128 v[200:203], v48 offset:36960
	ds_read_b128 v[204:207], v49
	ds_read_b128 v[208:211], v49 offset:36960
	v_cndmask_b32_e32 v48, v186, v247, vcc
	v_add3_u32 v62, v48, v187, v250
	ds_read2_b32 v[48:49], v62 offset0:95 offset1:96
	ds_read2_b32 v[50:51], v62 offset0:93 offset1:94
	ds_read2_b32 v[52:53], v62 offset0:87 offset1:88
	ds_read2_b32 v[54:55], v62 offset0:85 offset1:86
	ds_read2_b32 v[56:57], v62 offset0:79 offset1:80
	ds_read2_b32 v[58:59], v62 offset0:77 offset1:78
	ds_read2_b32 v[60:61], v62 offset0:71 offset1:72
	ds_read2_b32 v[62:63], v62 offset0:69 offset1:70
	s_and_b64 vcc, s[46:47], s[42:43]
	s_waitcnt lgkmcnt(7)
	v_mov_b32_e32 v65, v48
	v_cndmask_b32_e32 v48, v186, v248, vcc
	v_add3_u32 v48, v48, v187, v250
	s_waitcnt lgkmcnt(6)
	v_mov_b32_e32 v66, v51
	v_mov_b32_e32 v67, v50
	s_waitcnt lgkmcnt(5)
	v_mov_b32_e32 v68, v53
	v_mov_b32_e32 v69, v52
	s_waitcnt lgkmcnt(4)
	v_mov_b32_e32 v70, v55
	v_mov_b32_e32 v71, v54
	s_waitcnt lgkmcnt(3)
	v_mov_b32_e32 v72, v57
	v_mov_b32_e32 v73, v56
	s_waitcnt lgkmcnt(2)
	v_mov_b32_e32 v74, v59
	v_mov_b32_e32 v75, v58
	s_waitcnt lgkmcnt(1)
	v_mov_b32_e32 v76, v61
	v_mov_b32_e32 v77, v60
	s_waitcnt lgkmcnt(0)
	v_mov_b32_e32 v78, v63
	v_mov_b32_e32 v79, v62
	ds_read2_b32 v[50:51], v48 offset0:63 offset1:64
	ds_read2_b32 v[52:53], v48 offset0:61 offset1:62
	ds_read2_b32 v[54:55], v48 offset0:55 offset1:56
	ds_read2_b32 v[56:57], v48 offset0:53 offset1:54
	ds_read2_b32 v[58:59], v48 offset0:47 offset1:48
	ds_read2_b32 v[60:61], v48 offset0:45 offset1:46
	ds_read2_b32 v[62:63], v48 offset0:39 offset1:40
	ds_read2_b32 v[178:179], v48 offset0:37 offset1:38
	v_mov_b32_e32 v64, v49
	s_waitcnt lgkmcnt(7)
; #define LAS __attribute__((address_space(3)))
; __device__ __forceinline__ void attn_phase(LAS unsigned char* lds, const bf16_t* qp, const bf16_t* kvp, bf16_t* obuf, float* lse, const float* biasG, const int gi, const int rsh, const int G) {
;     ...
;         for (int c2 = 0; c2 < 5; c2 += 2) {
;             bf16x8 ka[4], kb[4];
; #pragma unroll
;             for (int d0 = 0; d0 < 4; ++d0) { ka[d0] = *(const LAS bf16x8*)(kbase + 2 * d0 * KCS + sc[c2] * 512); if (c2 + 1 < 5) kb[d0] = *(const LAS bf16x8*)(kbase + 2 * d0 * KCS + sc[c2 + 1 < 5 ? c2 + 1 : c2] * 512); }
; #pragma unroll
;             for (int q = 0; q < 2; ++q) { const int cc = c2 + q; if (cc < 5) { const bool dead = (np == 0) && (w + cc < 4);
;                 const LAS float* bq_ = dead ? bt + 27 - (160 + r32 - 32 * cc - 4 * hi) : bt;
; #pragma unroll
;                 for (int r = 0; r < 16; ++r) p[cc][r] = bq_[160 + r32 - 32 * cc - crow(r, hi)]; } }
;             __builtin_amdgcn_sched_barrier(0);
; #pragma unroll
;             for (int d0 = 0; d0 < 4; ++d0) {
;                 p[c2] = __builtin_amdgcn_mfma_f32_32x32x16_bf16(ka[d0], qr[d0], p[c2], 0, 0, 0);
;                 if (c2 + 1 < 5) p[c2 + 1 < 5 ? c2 + 1 : c2] = __builtin_amdgcn_mfma_f32_32x32x16_bf16(kb[d0], qr[d0], p[c2 + 1 < 5 ? c2 + 1 : c2], 0, 0, 0);
;             }
;             __builtin_amdgcn_sched_barrier(0);
;         }
;         float mx = p[0][0];
; #pragma unroll
;         for (int cc = 0; cc < 5; ++cc)
; #pragma unroll
;             for (int r = 0; r < 16; ++r) mx = fmaxf(mx, p[cc][r]);
;         mx = fmaxf(mx, __shfl_xor(mx, 32));
;         typedef float f32x2 __attribute__((ext_vector_type(2)));
;         f32x2 l2 = (f32x2){0.f, 0.f};
;     ...
;         ATT_EXP8(0, 0); ATT_EXP8(0, 8);
;         bf16_t* og = obuf + ((size_t)h * M + growq) * 64 + 8 * hi;
;         u32x4 prev[2][2];
;         f32x16 o[2];
; #pragma unroll
;         for (int r = 0; r < 16; ++r) { o[0][r] = 0.f; o[1][r] = 0.f; }
;         const LAS unsigned char* vb = lds + A_V0 + ((lane >> 4) & 1) * 32 + (lane & 3) * 8 + (4 * hi + ((lane & 15) >> 2)) * 64;
; #pragma unroll
;         for (int cc = 0; cc < 5; ++cc)
; #pragma unroll
;             for (int gk = 0; gk < 2; ++gk) {
;                 if (cc == 3 && gk == 0 && gi > 0) {
; #pragma unroll
;                     for (int d0 = 0; d0 < 2; ++d0)
; #pragma unroll
	v_mov_b32_e32 v48, v51
	v_mov_b32_e32 v49, v50
	s_waitcnt lgkmcnt(6)
	v_mov_b32_e32 v50, v53
	v_mov_b32_e32 v51, v52
	s_waitcnt lgkmcnt(5)
	v_mov_b32_e32 v52, v55
	v_mov_b32_e32 v53, v54
	s_waitcnt lgkmcnt(4)
	v_mov_b32_e32 v54, v57
	v_mov_b32_e32 v55, v56
	s_waitcnt lgkmcnt(3)
	v_mov_b32_e32 v56, v59
	v_mov_b32_e32 v57, v58
	s_waitcnt lgkmcnt(2)
	v_mov_b32_e32 v58, v61
	v_mov_b32_e32 v59, v60
	s_waitcnt lgkmcnt(1)
	v_mov_b32_e32 v60, v63
	v_mov_b32_e32 v61, v62
	s_waitcnt lgkmcnt(0)
	v_mov_b32_e32 v62, v179
	v_mov_b32_e32 v63, v178
	v_mfma_f32_32x32x16_bf16 v[64:79], v[182:185], v[28:31], v[64:79]
	s_nop 0
	v_mfma_f32_32x32x16_bf16 v[48:63], v[204:207], v[28:31], v[48:63]
	v_mfma_f32_32x32x16_bf16 v[64:79], v[32:35], v[24:27], v[64:79]
	v_mfma_f32_32x32x16_bf16 v[48:63], v[40:43], v[24:27], v[48:63]
	v_mfma_f32_32x32x16_bf16 v[64:79], v[36:39], v[20:23], v[64:79]
	v_mfma_f32_32x32x16_bf16 v[48:63], v[44:47], v[20:23], v[48:63]
	v_mfma_f32_32x32x16_bf16 v[64:79], v[200:203], v[16:19], v[64:79]
	v_mfma_f32_32x32x16_bf16 v[48:63], v[208:211], v[16:19], v[48:63]
	v_lshl_add_u32 v32, s4, 9, v243
	s_and_b64 vcc, s[46:47], s[44:45]
	ds_read_b128 v[182:185], v32 offset:12320
	ds_read_b128 v[200:203], v32 offset:24640
	ds_read_b128 v[204:207], v32
	ds_read_b128 v[208:211], v32 offset:36960
	v_cndmask_b32_e32 v32, v186, v249, vcc
	v_add3_u32 v32, v32, v187, v250
	ds_read2_b32 v[34:35], v32 offset0:31 offset1:32
	ds_read2_b32 v[36:37], v32 offset0:29 offset1:30
	ds_read2_b32 v[38:39], v32 offset0:23 offset1:24
	ds_read2_b32 v[40:41], v32 offset0:21 offset1:22
	ds_read2_b32 v[42:43], v32 offset0:15 offset1:16
	ds_read2_b32 v[44:45], v32 offset0:13 offset1:14
	ds_read2_b32 v[46:47], v32 offset0:7 offset1:8
	ds_read2_b32 v[178:179], v32 offset0:5 offset1:6
	s_waitcnt lgkmcnt(7)
	v_mov_b32_e32 v32, v35
	v_mov_b32_e32 v33, v34
	s_waitcnt lgkmcnt(6)
	v_mov_b32_e32 v34, v37
	v_mov_b32_e32 v35, v36
	s_waitcnt lgkmcnt(5)
	v_mov_b32_e32 v36, v39
	v_mov_b32_e32 v37, v38
	s_waitcnt lgkmcnt(4)
	v_mov_b32_e32 v38, v41
	v_mov_b32_e32 v39, v40
	s_waitcnt lgkmcnt(3)
	v_mov_b32_e32 v40, v43
	v_mov_b32_e32 v41, v42
	s_waitcnt lgkmcnt(2)
	v_mov_b32_e32 v42, v45
	v_mov_b32_e32 v43, v44
	s_waitcnt lgkmcnt(1)
	v_mov_b32_e32 v44, v47
	v_mov_b32_e32 v45, v46
	s_waitcnt lgkmcnt(0)
	v_mov_b32_e32 v46, v179
	v_mov_b32_e32 v47, v178
	s_nop 1
	v_mfma_f32_32x32x16_bf16 v[32:47], v[204:207], v[28:31], v[32:47]
	v_mfma_f32_32x32x16_bf16 v[32:47], v[182:185], v[24:27], v[32:47]
	v_mfma_f32_32x32x16_bf16 v[32:47], v[200:203], v[20:23], v[32:47]
	v_mfma_f32_32x32x16_bf16 v[32:47], v[208:211], v[16:19], v[32:47]
	v_max_f32_e32 v16, v1, v1
	v_max_f32_e32 v17, v0, v0
	v_max_f32_e32 v16, v17, v16
	v_max3_f32 v16, v16, v2, v3
	v_max3_f32 v16, v16, v4, v5
	v_max3_f32 v16, v16, v6, v7
	v_max3_f32 v16, v16, v8, v9
	v_max3_f32 v16, v16, v10, v11
	v_max3_f32 v16, v16, v12, v13
	v_max3_f32 v16, v16, v14, v15
	v_max3_f32 v16, v16, v80, v81
	v_max3_f32 v16, v16, v82, v83
	v_max3_f32 v16, v16, v84, v85
	v_max3_f32 v16, v16, v86, v87
	v_max3_f32 v16, v16, v88, v89
	v_max3_f32 v16, v16, v90, v91
	v_max3_f32 v16, v16, v92, v93
	v_max3_f32 v16, v16, v94, v95
	v_max3_f32 v16, v16, v64, v65
	v_max3_f32 v16, v16, v66, v67
	v_max3_f32 v16, v16, v68, v69
	v_max3_f32 v16, v16, v70, v71
	v_max3_f32 v16, v16, v72, v73
	v_max3_f32 v16, v16, v74, v75
	v_max3_f32 v16, v16, v76, v77
	v_max3_f32 v16, v16, v78, v79
	v_max3_f32 v16, v16, v48, v49
	v_max3_f32 v16, v16, v50, v51
	v_max3_f32 v16, v16, v52, v53
	v_max3_f32 v16, v16, v54, v55
	v_max3_f32 v16, v16, v56, v57
	v_max3_f32 v16, v16, v58, v59
	v_max3_f32 v16, v16, v60, v61
	v_max3_f32 v16, v16, v62, v63
	v_max3_f32 v16, v16, v32, v33
	v_max3_f32 v16, v16, v34, v35
	v_max3_f32 v16, v16, v36, v37
	v_max3_f32 v16, v16, v38, v39
	v_and_b32_e32 v18, 64, v233
	v_max3_f32 v16, v16, v40, v41
	v_xor_b32_e32 v17, 32, v233
	v_add_u32_e32 v18, 64, v18
	v_max3_f32 v16, v16, v42, v43
	v_cmp_lt_i32_e32 vcc, v17, v18
	v_max3_f32 v16, v16, v44, v45
	v_max3_f32 v16, v16, v46, v47
	v_cndmask_b32_e32 v17, v233, v17, vcc
	v_lshlrev_b32_e32 v228, 2, v17
	ds_bpermute_b32 v17, v228, v16
	s_lshl_b32 s2, s19, 22
	v_readlane_b32 s3, v255, 21
	s_add_u32 s2, s3, s2
	v_readlane_b32 s3, v255, 22
	s_waitcnt lgkmcnt(0)
	v_max_f32_e32 v17, v17, v17
	v_max_f32_e32 v200, v16, v17
	v_sub_f32_e32 v0, v0, v200
	v_sub_f32_e32 v1, v1, v200
	s_addc_u32 s3, s3, 0
	v_exp_f32_e32 v202, v0
	v_exp_f32_e32 v203, v1
	v_sub_f32_e32 v0, v2, v200
	v_sub_f32_e32 v1, v3, v200
	v_mov_b32_e32 v191, v96
	v_exp_f32_e32 v204, v0
	v_exp_f32_e32 v205, v1
	v_sub_f32_e32 v0, v4, v200
	v_sub_f32_e32 v1, v5, v200
	v_lshl_add_u32 v178, s27, 11, v244
	v_exp_f32_e32 v206, v0
	v_exp_f32_e32 v207, v1
	v_sub_f32_e32 v0, v6, v200
	v_sub_f32_e32 v1, v7, v200
	v_add_u32_e32 v179, 0xc080, v178
	v_exp_f32_e32 v208, v0
	v_exp_f32_e32 v209, v1
	v_sub_f32_e32 v0, v8, v200
	v_sub_f32_e32 v1, v9, v200
	v_sub_f32_e32 v64, v64, v200
	v_sub_f32_e32 v65, v65, v200
	v_exp_f32_e32 v210, v0
	v_exp_f32_e32 v211, v1
	v_sub_f32_e32 v0, v10, v200
	v_sub_f32_e32 v1, v11, v200
	s_and_b64 vcc, exec, s[54:55]
	v_exp_f32_e32 v212, v0
	v_exp_f32_e32 v213, v1
	v_sub_f32_e32 v0, v12, v200
	v_sub_f32_e32 v1, v13, v200
	s_nop 0
	v_exp_f32_e32 v214, v0
	v_exp_f32_e32 v215, v1
	v_sub_f32_e32 v0, v14, v200
	v_sub_f32_e32 v1, v15, v200
	s_nop 0
	v_exp_f32_e32 v216, v0
	v_exp_f32_e32 v217, v1
	v_lshlrev_b64 v[0:1], 7, v[198:199]
	v_lshl_add_u64 v[0:1], s[2:3], 0, v[0:1]
	v_lshl_add_u64 v[198:199], v[0:1], 0, v[190:191]
	v_sub_f32_e32 v0, v80, v200
	v_sub_f32_e32 v1, v81, v200
	s_nop 0
	v_exp_f32_e32 v80, v0
	v_exp_f32_e32 v81, v1
	v_sub_f32_e32 v0, v82, v200
	v_sub_f32_e32 v1, v83, v200
	s_nop 0
	v_exp_f32_e32 v218, v0
	v_exp_f32_e32 v219, v1
	v_sub_f32_e32 v0, v84, v200
	v_sub_f32_e32 v1, v85, v200
	s_nop 0
	v_exp_f32_e32 v84, v0
	v_exp_f32_e32 v85, v1
	v_sub_f32_e32 v0, v86, v200
	v_sub_f32_e32 v1, v87, v200
	v_sub_f32_e32 v86, v88, v200
	v_sub_f32_e32 v87, v89, v200
	v_exp_f32_e32 v82, v0
	v_exp_f32_e32 v83, v1
	v_cvt_pk_bf16_f32 v0, v202, v203
	v_cvt_pk_bf16_f32 v1, v204, v205
	v_cvt_pk_bf16_f32 v2, v206, v207
	v_cvt_pk_bf16_f32 v3, v208, v209
	ds_read_b64_tr_b16 v[4:5], v178 offset:49280
	ds_read_b64_tr_b16 v[6:7], v178 offset:49792
	s_waitcnt lgkmcnt(0)
; __device__ __forceinline__ unsigned cvt_pk_bf16(float lo, float hi) { unsigned r; asm volatile("v_cvt_pk_bf16_f32 %0, %1, %2" : "=v"(r) : "v"(lo), "v"(hi)); return r; }
; #define LAS __attribute__((address_space(3)))
; __device__ __forceinline__ v4i16_t vtr(const LAS unsigned char* p) { return __builtin_amdgcn_ds_read_tr16_b64_v4i16((LAS v4i16_t*)p); }
; __device__ __forceinline__ void attn_phase(LAS unsigned char* lds, const bf16_t* qp, const bf16_t* kvp, bf16_t* obuf, float* lse, const float* biasG, const int gi, const int rsh, const int G) {
;     ...
;         ATT_EXP8(0, 0); ATT_EXP8(0, 8);
;         bf16_t* og = obuf + ((size_t)h * M + growq) * 64 + 8 * hi;
;         u32x4 prev[2][2];
;         f32x16 o[2];
; #pragma unroll
;         for (int r = 0; r < 16; ++r) { o[0][r] = 0.f; o[1][r] = 0.f; }
;         const LAS unsigned char* vb = lds + A_V0 + ((lane >> 4) & 1) * 32 + (lane & 3) * 8 + (4 * hi + ((lane & 15) >> 2)) * 64;
; #pragma unroll
;         for (int cc = 0; cc < 5; ++cc)
; #pragma unroll
;             for (int gk = 0; gk < 2; ++gk) {
;                 if (cc == 3 && gk == 0 && gi > 0) {
; #pragma unroll
;                     for (int d0 = 0; d0 < 2; ++d0)
; #pragma unroll
;                         for (int pr = 0; pr < 2; ++pr) prev[d0][pr] = gld<u32x4>(og + 32 * d0 + 16 * pr);
;                 }
;                 if (cc + 1 < 5) ATT_EXP8(cc + 1 < 5 ? cc + 1 : cc, 8 * gk);
;                 u32x4 pw; pw.x = cvt_pk_bf16(p[cc][8 * gk + 0], p[cc][8 * gk + 1]); pw.y = cvt_pk_bf16(p[cc][8 * gk + 2], p[cc][8 * gk + 3]);
;                 pw.z = cvt_pk_bf16(p[cc][8 * gk + 4], p[cc][8 * gk + 5]); pw.w = cvt_pk_bf16(p[cc][8 * gk + 6], p[cc][8 * gk + 7]);
;                 const bf16x8 pa = __builtin_bit_cast(bf16x8, pw);
;                 const LAS unsigned char* vrow = vb + sc[cc] * 2048 + gk * 1024;
; #pragma unroll
;                 for (int d0 = 0; d0 < 2; ++d0) {
;                     const v4i16_t lo = vtr(vrow + d0 * VHS), hh = vtr(vrow + d0 * VHS + 512);
;                     const bf16x8 vf = (bf16x8){lo[0], lo[1], lo[2], lo[3], hh[0], hh[1], hh[2], hh[3]};
;                     o[d0] = __builtin_amdgcn_mfma_f32_32x32x16_bf16(vf, pa, o[d0], 0, 0, 0);
;                 }
;             }
	v_mfma_f32_32x32x16_bf16 v[16:31], v[4:7], v[0:3], 0
	ds_read_b64_tr_b16 v[4:5], v179 offset:24640
	ds_read_b64_tr_b16 v[6:7], v179 offset:25152
	v_exp_f32_e32 v220, v86
	v_exp_f32_e32 v221, v87
	v_sub_f32_e32 v86, v90, v200
	v_sub_f32_e32 v87, v91, v200
	s_nop 0
	v_exp_f32_e32 v90, v86
	v_exp_f32_e32 v91, v87
	v_sub_f32_e32 v86, v92, v200
	v_sub_f32_e32 v87, v93, v200
	v_cvt_pk_bf16_f32 v92, v210, v211
	v_cvt_pk_bf16_f32 v93, v212, v213
	s_waitcnt lgkmcnt(0)
	v_mfma_f32_32x32x16_bf16 v[0:15], v[4:7], v[0:3], 0
	v_exp_f32_e32 v88, v86
	v_exp_f32_e32 v89, v87
	v_sub_f32_e32 v86, v94, v200
	v_sub_f32_e32 v87, v95, v200
	v_cvt_pk_bf16_f32 v94, v214, v215
	v_cvt_pk_bf16_f32 v95, v216, v217
	ds_read_b64_tr_b16 v[182:183], v178 offset:50304
	ds_read_b64_tr_b16 v[184:185], v178 offset:50816
	v_lshl_add_u32 v178, s26, 11, v244
	s_waitcnt lgkmcnt(0)
	v_mfma_f32_32x32x16_bf16 v[16:31], v[182:185], v[92:95], v[16:31]
	ds_read_b64_tr_b16 v[182:183], v179 offset:25664
	ds_read_b64_tr_b16 v[184:185], v179 offset:26176
	v_add_u32_e32 v179, 0xc080, v178
	v_exp_f32_e32 v86, v86
	v_exp_f32_e32 v87, v87
	s_waitcnt lgkmcnt(0)
	v_mfma_f32_32x32x16_bf16 v[0:15], v[182:185], v[92:95], v[0:15]
	v_exp_f32_e32 v94, v64
	v_exp_f32_e32 v95, v65
	v_sub_f32_e32 v64, v66, v200
	v_sub_f32_e32 v65, v67, v200
	s_nop 0
	v_exp_f32_e32 v92, v64
	v_exp_f32_e32 v93, v65
	v_sub_f32_e32 v64, v68, v200
	v_sub_f32_e32 v65, v69, v200
	v_cvt_pk_bf16_f32 v68, v80, v81
	v_cvt_pk_bf16_f32 v69, v218, v219
	s_nop 0
	v_exp_f32_e32 v66, v64
	v_exp_f32_e32 v67, v65
	v_sub_f32_e32 v64, v70, v200
	v_sub_f32_e32 v65, v71, v200
	v_cvt_pk_bf16_f32 v70, v84, v85
	v_cvt_pk_bf16_f32 v71, v82, v83
	ds_read_b64_tr_b16 v[182:183], v178 offset:49280
	ds_read_b64_tr_b16 v[184:185], v178 offset:49792
	s_waitcnt lgkmcnt(0)
	v_mfma_f32_32x32x16_bf16 v[16:31], v[182:185], v[68:71], v[16:31]
	ds_read_b64_tr_b16 v[182:183], v179 offset:24640
	ds_read_b64_tr_b16 v[184:185], v179 offset:25152
	v_exp_f32_e32 v64, v64
	v_exp_f32_e32 v65, v65
	s_waitcnt lgkmcnt(0)
	v_mfma_f32_32x32x16_bf16 v[0:15], v[182:185], v[68:71], v[0:15]
	v_add_f32_e64 v68, v72, -v200
	v_add_f32_e64 v69, v73, -v200
	v_exp_f32_e32 v222, v68
	v_exp_f32_e32 v223, v69
	v_sub_f32_e32 v68, v74, v200
	v_sub_f32_e32 v69, v75, v200
	v_cvt_pk_bf16_f32 v74, v220, v221
	v_cvt_pk_bf16_f32 v75, v90, v91
	s_nop 0
	v_exp_f32_e32 v72, v68
	v_exp_f32_e32 v73, v69
	v_sub_f32_e32 v68, v76, v200
	v_sub_f32_e32 v69, v77, v200
	v_cvt_pk_bf16_f32 v76, v88, v89
	v_cvt_pk_bf16_f32 v77, v86, v87
	ds_read_b64_tr_b16 v[182:183], v178 offset:50304
	ds_read_b64_tr_b16 v[184:185], v178 offset:50816
	s_waitcnt lgkmcnt(0)
	v_mfma_f32_32x32x16_bf16 v[16:31], v[182:185], v[74:77], v[16:31]
	ds_read_b64_tr_b16 v[182:183], v179 offset:25664
	ds_read_b64_tr_b16 v[184:185], v179 offset:26176
	v_exp_f32_e32 v70, v68
	v_exp_f32_e32 v71, v69
	v_sub_f32_e32 v68, v78, v200
	v_sub_f32_e32 v69, v79, v200
	v_lshl_add_u32 v78, s23, 11, v244
	v_add_u32_e32 v79, 0xc080, v78
	v_exp_f32_e32 v68, v68
	s_waitcnt lgkmcnt(0)
	v_mfma_f32_32x32x16_bf16 v[0:15], v[182:185], v[74:77], v[0:15]
	v_cvt_pk_bf16_f32 v74, v94, v95
	v_cvt_pk_bf16_f32 v75, v92, v93
	v_cvt_pk_bf16_f32 v76, v66, v67
	v_cvt_pk_bf16_f32 v77, v64, v65
	ds_read_b64_tr_b16 v[182:183], v78 offset:49280
	ds_read_b64_tr_b16 v[184:185], v78 offset:49792
	v_exp_f32_e32 v69, v69
	s_waitcnt lgkmcnt(0)
	v_mfma_f32_32x32x16_bf16 v[16:31], v[182:185], v[74:77], v[16:31]
	ds_read_b64_tr_b16 v[182:183], v79 offset:24640
	ds_read_b64_tr_b16 v[184:185], v79 offset:25152
	s_waitcnt lgkmcnt(0)
	v_mfma_f32_32x32x16_bf16 v[0:15], v[182:185], v[74:77], v[0:15]
	v_cvt_pk_bf16_f32 v74, v222, v223
	v_cvt_pk_bf16_f32 v75, v72, v73
	v_cvt_pk_bf16_f32 v76, v70, v71
	v_cvt_pk_bf16_f32 v77, v68, v69
	ds_read_b64_tr_b16 v[182:183], v78 offset:50304
	ds_read_b64_tr_b16 v[184:185], v78 offset:50816
	s_waitcnt lgkmcnt(0)
	v_mfma_f32_32x32x16_bf16 v[16:31], v[182:185], v[74:77], v[16:31]
	ds_read_b64_tr_b16 v[182:183], v79 offset:25664
	ds_read_b64_tr_b16 v[184:185], v79 offset:26176
	s_waitcnt lgkmcnt(0)
	v_mfma_f32_32x32x16_bf16 v[0:15], v[182:185], v[74:77], v[0:15]
	s_cbranch_vccnz .LBB0_117
	global_load_dwordx4 v[158:161], v[198:199], off
	global_load_dwordx4 v[154:157], v[198:199], off offset:32
	global_load_dwordx4 v[150:153], v[198:199], off offset:64
	global_load_dwordx4 v[146:149], v[198:199], off offset:96
; __device__ __forceinline__ unsigned cvt_pk_bf16(float lo, float hi) { unsigned r; asm volatile("v_cvt_pk_bf16_f32 %0, %1, %2" : "=v"(r) : "v"(lo), "v"(hi)); return r; }
; #define LAS __attribute__((address_space(3)))
; __device__ __forceinline__ void attn_phase(LAS unsigned char* lds, const bf16_t* qp, const bf16_t* kvp, bf16_t* obuf, float* lse, const float* biasG, const int gi, const int rsh, const int G) {
;     ...
;         ATT_EXP8(0, 0); ATT_EXP8(0, 8);
;         bf16_t* og = obuf + ((size_t)h * M + growq) * 64 + 8 * hi;
;         u32x4 prev[2][2];
;         f32x16 o[2];
; #pragma unroll
;         for (int r = 0; r < 16; ++r) { o[0][r] = 0.f; o[1][r] = 0.f; }
;         const LAS unsigned char* vb = lds + A_V0 + ((lane >> 4) & 1) * 32 + (lane & 3) * 8 + (4 * hi + ((lane & 15) >> 2)) * 64;
; #pragma unroll
;         for (int cc = 0; cc < 5; ++cc)
; #pragma unroll
;             for (int gk = 0; gk < 2; ++gk) {
;                 if (cc == 3 && gk == 0 && gi > 0) {
; #pragma unroll
;                     for (int d0 = 0; d0 < 2; ++d0)
; #pragma unroll
;                         for (int pr = 0; pr < 2; ++pr) prev[d0][pr] = gld<u32x4>(og + 32 * d0 + 16 * pr);
;                 }
;                 if (cc + 1 < 5) ATT_EXP8(cc + 1 < 5 ? cc + 1 : cc, 8 * gk);
;                 u32x4 pw; pw.x = cvt_pk_bf16(p[cc][8 * gk + 0], p[cc][8 * gk + 1]); pw.y = cvt_pk_bf16(p[cc][8 * gk + 2], p[cc][8 * gk + 3]);
;                 pw.z = cvt_pk_bf16(p[cc][8 * gk + 4], p[cc][8 * gk + 5]); pw.w = cvt_pk_bf16(p[cc][8 * gk + 6], p[cc][8 * gk + 7]);
;                 const bf16x8 pa = __builtin_bit_cast(bf16x8, pw);
;                 const LAS unsigned char* vrow = vb + sc[cc] * 2048 + gk * 1024;
; #pragma unroll
;                 for (int d0 = 0; d0 < 2; ++d0) {
;                     const v4i16_t lo = vtr(vrow + d0 * VHS), hh = vtr(vrow + d0 * VHS + 512);
;                     const bf16x8 vf = (bf16x8){lo[0], lo[1], lo[2], lo[3], hh[0], hh[1], hh[2], hh[3]};
;                     o[d0] = __builtin_amdgcn_mfma_f32_32x32x16_bf16(vf, pa, o[d0], 0, 0, 0);
;                 }
;             }
;     ...
;         float l = l2.x + l2.y;
;         l += __shfl_xor(l, 32);
;         const float lse_new = mx + __builtin_amdgcn_logf(l);
;         float ca = 0.f, cb = 1.0f / l, lse_out = lse_new;
.LBB0_117:
	v_add_f32_e32 v74, 0, v202
	v_add_f32_e32 v75, 0, v203
	v_mov_b32_e32 v201, v200
	v_add_f32_e32 v74, v204, v74
	v_add_f32_e32 v75, v205, v75
	v_sub_f32_e32 v48, v48, v200
	v_sub_f32_e32 v49, v49, v201
	v_add_f32_e32 v74, v206, v74
	v_add_f32_e32 v75, v207, v75
	v_exp_f32_e32 v48, v48
	v_add_f32_e32 v74, v208, v74
	v_add_f32_e32 v75, v209, v75
	v_exp_f32_e32 v49, v49
	v_add_f32_e32 v74, v210, v74
	v_add_f32_e32 v75, v211, v75
	v_sub_f32_e32 v50, v50, v200
	v_sub_f32_e32 v51, v51, v201
	v_add_f32_e32 v74, v212, v74
	v_add_f32_e32 v75, v213, v75
	v_exp_f32_e32 v50, v50
	v_add_f32_e32 v74, v214, v74
	v_add_f32_e32 v75, v215, v75
	v_exp_f32_e32 v51, v51
	v_add_f32_e32 v74, v216, v74
	v_add_f32_e32 v75, v217, v75
	v_sub_f32_e32 v52, v52, v200
	v_sub_f32_e32 v53, v53, v201
	v_add_f32_e32 v74, v80, v74
	v_add_f32_e32 v75, v81, v75
	v_exp_f32_e32 v52, v52
	v_add_f32_e32 v74, v218, v74
	v_add_f32_e32 v75, v219, v75
	v_exp_f32_e32 v53, v53
	v_add_f32_e32 v74, v84, v74
	v_add_f32_e32 v75, v85, v75
	v_sub_f32_e32 v54, v54, v200
	v_sub_f32_e32 v55, v55, v201
	v_add_f32_e32 v74, v82, v74
	v_add_f32_e32 v75, v83, v75
	v_exp_f32_e32 v54, v54
	v_add_f32_e32 v74, v220, v74
	v_add_f32_e32 v75, v221, v75
	v_exp_f32_e32 v55, v55
	v_add_f32_e32 v74, v90, v74
	v_add_f32_e32 v75, v91, v75
	v_sub_f32_e32 v56, v56, v200
	v_sub_f32_e32 v57, v57, v201
	v_add_f32_e32 v74, v88, v74
	v_add_f32_e32 v75, v89, v75
	v_exp_f32_e32 v56, v56
	v_add_f32_e32 v74, v86, v74
	v_add_f32_e32 v75, v87, v75
	v_exp_f32_e32 v57, v57
	v_add_f32_e32 v74, v94, v74
	v_add_f32_e32 v75, v95, v75
	v_sub_f32_e32 v58, v58, v200
	v_sub_f32_e32 v59, v59, v201
	v_add_f32_e32 v74, v92, v74
	v_add_f32_e32 v75, v93, v75
	v_sub_f32_e32 v32, v32, v200
	v_sub_f32_e32 v33, v33, v201
	v_add_f32_e32 v66, v66, v74
	v_add_f32_e32 v67, v67, v75
	v_exp_f32_e32 v58, v58
	v_add_f32_e32 v64, v64, v66
	v_add_f32_e32 v65, v65, v67
	v_exp_f32_e32 v59, v59
	v_add_f32_e32 v64, v222, v64
	v_add_f32_e32 v65, v223, v65
	v_sub_f32_e32 v60, v60, v200
	v_sub_f32_e32 v61, v61, v201
	v_add_f32_e32 v64, v72, v64
	v_add_f32_e32 v65, v73, v65
	v_lshl_add_u32 v72, s22, 11, v244
	v_add_f32_e32 v64, v70, v64
	v_add_f32_e32 v65, v71, v65
	v_exp_f32_e32 v66, v32
	v_add_f32_e32 v64, v68, v64
	v_add_f32_e32 v65, v69, v65
	v_exp_f32_e32 v67, v33
	v_add_f32_e32 v64, v48, v64
	v_add_f32_e32 v65, v49, v65
	v_sub_f32_e32 v32, v34, v200
	v_sub_f32_e32 v33, v35, v201
	v_add_f32_e32 v64, v50, v64
	v_add_f32_e32 v65, v51, v65
	v_add_u32_e32 v73, 0xc080, v72
	v_add_f32_e32 v64, v52, v64
	v_add_f32_e32 v65, v53, v65
	v_exp_f32_e32 v60, v60
	v_add_f32_e32 v64, v54, v64
	v_add_f32_e32 v65, v55, v65
	v_exp_f32_e32 v61, v61
	v_sub_f32_e32 v62, v62, v200
	v_sub_f32_e32 v63, v63, v201
	v_cvt_pk_bf16_f32 v48, v48, v49
	v_cvt_pk_bf16_f32 v49, v50, v51
	v_cvt_pk_bf16_f32 v50, v52, v53
	v_cvt_pk_bf16_f32 v51, v54, v55
	ds_read_b64_tr_b16 v[52:53], v72 offset:49280
	ds_read_b64_tr_b16 v[54:55], v72 offset:49792
	v_exp_f32_e32 v68, v32
	v_exp_f32_e32 v69, v33
	ds_read_b64_tr_b16 v[32:33], v73 offset:24640
	ds_read_b64_tr_b16 v[34:35], v73 offset:25152
	v_exp_f32_e32 v62, v62
	v_exp_f32_e32 v63, v63
	v_add_f32_e32 v64, v56, v64
	v_add_f32_e32 v65, v57, v65
	v_sub_f32_e32 v36, v36, v200
	v_sub_f32_e32 v37, v37, v201
	v_add_f32_e32 v64, v58, v64
	v_add_f32_e32 v65, v59, v65
	v_exp_f32_e32 v70, v36
	v_add_f32_e32 v64, v60, v64
	v_add_f32_e32 v65, v61, v65
	v_exp_f32_e32 v71, v37
	v_add_f32_e32 v64, v62, v64
	v_add_f32_e32 v65, v63, v65
	v_sub_f32_e32 v36, v38, v200
	v_sub_f32_e32 v37, v39, v201
	s_waitcnt lgkmcnt(0)
	v_mfma_f32_32x32x16_bf16 v[0:15], v[32:35], v[48:51], v[0:15]
	v_add_f32_e64 v40, v40, -v200
	v_add_f32_e64 v41, v41, -v201
	v_cvt_pk_bf16_f32 v32, v56, v57
	v_cvt_pk_bf16_f32 v33, v58, v59
	v_cvt_pk_bf16_f32 v34, v60, v61
	v_cvt_pk_bf16_f32 v35, v62, v63
	v_add_f32_e64 v44, v44, -v200
	v_add_f32_e64 v45, v45, -v201
	v_exp_f32_e32 v56, v40
	v_mfma_f32_32x32x16_bf16 v[16:31], v[52:55], v[48:51], v[16:31]
	v_exp_f32_e32 v52, v36
	v_exp_f32_e32 v53, v37
	v_add_f32_e32 v36, v66, v64
	v_add_f32_e32 v37, v67, v65
	v_exp_f32_e32 v57, v41
	v_add_f32_e32 v36, v68, v36
	v_add_f32_e32 v37, v69, v37
	v_sub_f32_e32 v40, v42, v200
	v_sub_f32_e32 v41, v43, v201
	v_add_f32_e32 v54, v70, v36
	v_add_f32_e32 v55, v71, v37
	ds_read_b64_tr_b16 v[36:37], v72 offset:50304
	ds_read_b64_tr_b16 v[38:39], v72 offset:50816
	v_exp_f32_e32 v58, v40
	v_exp_f32_e32 v59, v41
	ds_read_b64_tr_b16 v[40:41], v73 offset:25664
	ds_read_b64_tr_b16 v[42:43], v73 offset:26176
	s_waitcnt lgkmcnt(0)
	v_mfma_f32_32x32x16_bf16 v[0:15], v[40:43], v[32:35], v[0:15]
	v_lshl_add_u32 v64, s4, 11, v244
	v_add_u32_e32 v65, 0xc080, v64
	v_exp_f32_e32 v60, v44
	v_exp_f32_e32 v61, v45
	v_sub_f32_e32 v40, v46, v200
	v_sub_f32_e32 v41, v47, v201
	s_and_b64 vcc, exec, s[54:55]
	v_exp_f32_e32 v62, v40
	v_mfma_f32_32x32x16_bf16 v[16:31], v[36:39], v[32:35], v[16:31]
	v_cvt_pk_bf16_f32 v36, v66, v67
	v_cvt_pk_bf16_f32 v37, v68, v69
	v_cvt_pk_bf16_f32 v38, v70, v71
	v_cvt_pk_bf16_f32 v39, v52, v53
	ds_read_b64_tr_b16 v[48:49], v64 offset:49280
	ds_read_b64_tr_b16 v[50:51], v64 offset:49792
	ds_read_b64_tr_b16 v[32:33], v65 offset:24640
	ds_read_b64_tr_b16 v[34:35], v65 offset:25152
	v_exp_f32_e32 v63, v41
	s_waitcnt lgkmcnt(0)
	v_mfma_f32_32x32x16_bf16 v[0:15], v[32:35], v[36:39], v[0:15]
	v_add_f32_e64 v32, v52, v54
	v_add_f32_e64 v33, v53, v55
	v_cvt_pk_bf16_f32 v40, v56, v57
	v_cvt_pk_bf16_f32 v41, v58, v59
	v_cvt_pk_bf16_f32 v42, v60, v61
	v_cvt_pk_bf16_f32 v43, v62, v63
	ds_read_b64_tr_b16 v[44:45], v64 offset:50304
	ds_read_b64_tr_b16 v[46:47], v64 offset:50816
	v_add_f32_e64 v32, v56, v32
	v_add_f32_e64 v33, v57, v33
	v_mfma_f32_32x32x16_bf16 v[16:31], v[48:51], v[36:39], v[16:31]
	v_add_f32_e64 v32, v58, v32
	v_add_f32_e64 v33, v59, v33
	ds_read_b64_tr_b16 v[36:37], v65 offset:25664
	ds_read_b64_tr_b16 v[38:39], v65 offset:26176
	v_add_f32_e64 v32, v60, v32
	v_add_f32_e64 v33, v61, v33
	v_add_f32_e32 v32, v62, v32
	v_add_f32_e32 v33, v63, v33
	s_nop 0
	v_add_f32_e32 v32, v32, v33
	ds_bpermute_b32 v33, v228, v32
	s_waitcnt lgkmcnt(3)
	v_mfma_f32_32x32x16_bf16 v[16:31], v[44:47], v[40:43], v[16:31]
	s_waitcnt lgkmcnt(0)
	v_add_f32_e32 v34, v32, v33
	v_log_f32_e32 v32, v34
	s_nop 0
	v_add_f32_e32 v35, v200, v32
	v_mfma_f32_32x32x16_bf16 v[0:15], v[36:39], v[40:43], v[0:15]
	s_cbranch_vccnz .LBB0_119
; __device__ __forceinline__ void attn_phase(LAS unsigned char* lds, const bf16_t* qp, const bf16_t* kvp, bf16_t* obuf, float* lse, const float* biasG, const int gi, const int rsh, const int G) {
;     ...
;         float l = l2.x + l2.y;
;         l += __shfl_xor(l, 32);
;         const float lse_new = mx + __builtin_amdgcn_logf(l);
;         float ca = 0.f, cb = 1.0f / l, lse_out = lse_new;
;         if (gi > 0) {
;             const float mm = fmaxf(lp, lse_new);
;             const float wa = __builtin_amdgcn_exp2f(lp - mm), wb = __builtin_amdgcn_exp2f(lse_new - mm), tot = wa + wb, it = 1.0f / tot;
;             ca = wa * it; cb = wb * it / l; lse_out = mm + __builtin_amdgcn_logf(tot);
;         }
	v_max_f32_e32 v32, v35, v35
	s_waitcnt vmcnt(16)
	v_max_f32_e32 v33, v252, v252
	v_max_f32_e32 v37, v33, v32
	v_sub_f32_e32 v32, v252, v37
	v_exp_f32_e32 v33, v32
	v_sub_f32_e32 v32, v35, v37
	v_exp_f32_e32 v32, v32
	v_mov_b32_e32 v252, 0x1fcf
	v_add_f32_e32 v35, v33, v32
	v_div_scale_f32 v36, s[2:3], v35, v35, 1.0
	v_rcp_f32_e32 v38, v36
	v_div_scale_f32 v39, vcc, 1.0, v35, 1.0
	v_fma_f32 v40, -v36, v38, 1.0
	v_fmac_f32_e32 v38, v40, v38
	v_mul_f32_e32 v40, v39, v38
	v_fma_f32 v41, -v36, v40, v39
	v_fmac_f32_e32 v40, v41, v38
	v_fma_f32 v36, -v36, v40, v39
	v_log_f32_e32 v39, v35
	v_div_fmas_f32 v36, v36, v38, v40
	v_div_fixup_f32 v36, v36, v35, 1.0
	v_pk_mul_f32 v[32:33], v[32:33], v[36:37] op_sel_hi:[1,0]
	v_add_f32_e32 v35, v37, v39
	s_and_saveexec_b64 s[28:29], s[98:99]
	s_cbranch_execnz .LBB0_120
	s_branch .LBB0_121
